# attention: halves of the diagonal KV block that are fully visible to a wave's query rows take the mask-free path (mask code only for the one partially masked half per wave)
# speedup vs baseline: 1.0033x; 1.0033x over previous
; #define LAS __attribute__((address_space(3)))
; __device__ __forceinline__ int crow(int r, int hi) { return (r & 3) + 8 * (r >> 2) + 4 * hi; }
; __device__ __forceinline__ void attn_unit(const Params& p, LAS unsigned char* lds, int bh, int qb, float mshift, int tid, int lane, int wave) {
;     ...
;             if (jb >= 0 && 64 * jb + 32 * kh > 32 * wave + 31) continue;
;             f32x16 C;
; #pragma unroll
;             for (int i = 0; i < 16; ++i) C[i] = -mshift;
;             const LAS unsigned char* kr = bb + AB_K + (32 * kh + r32) * 144 + hi * 16;
; #pragma unroll
;             for (int d0 = 0; d0 < 4; ++d0) { const bf16x8 a = *(const LAS bf16x8*)(kr + d0 * 32); C = __builtin_amdgcn_mfma_f32_32x32x16_bf16(a, qr[d0], C, 0, 0, 0); }
;             { u32x4 t = *(const LAS u32x4*)(bb + AB_A + (32 * kh + r32) * 16); if (hi) t = (u32x4){0u, 0u, 0u, 0u};
;               C = __builtin_amdgcn_mfma_f32_32x32x16_bf16(__builtin_bit_cast(bf16x8, t), qa, C, 0, 0, 0); }
;             if (jb >= 0) {
; #pragma unroll
;                 for (int i = 0; i < 16; ++i) { const int kv = 64 * jb + 32 * kh + crow(i, hi); if (kv > q_rel) C[i] = -INFINITY; }
;             }
.LBB0_362:
	s_or_b64 exec, exec, s[10:11]
	s_bitcmp1_b32 s47, 0
	s_cselect_b32 s0, 0x4c00, 0
	s_add_i32 s51, s0, 0
	s_add_i32 s0, s50, s47
	s_cmp_gt_i32 s0, -1
	s_cselect_b64 s[38:39], -1, 0
	s_cmp_gt_u32 s49, s5
	s_cselect_b64 s[10:11], -1, 0
	v_add_u32_e32 v123, s51, v104
	v_cndmask_b32_e64 v48, 0, 1, s[38:39]
	s_and_b64 s[10:11], s[38:39], s[10:11]
	v_add_u32_e32 v121, s49, v177
	s_and_b64 vcc, exec, s[10:11]
	v_add_u32_e32 v119, v123, v178
	v_cmp_ne_u32_e64 s[10:11], 1, v48
	s_cbranch_vccnz .LBB0_366
	ds_read_b128 v[184:187], v119
	v_add_u32_e32 v48, s51, v179
	ds_read_b128 v[188:191], v48 offset:18432
	s_add_i32 s54, s49, 32
	s_cmp_le_i32 s54, s4
	s_cselect_b64 vcc, exec, 0
	s_waitcnt lgkmcnt(1)
	v_mfma_f32_32x32x16_bf16 v[48:63], v[184:187], v[80:83], v[0:15]
	ds_read_b128 v[184:187], v119 offset:32
	ds_read_b128 v[192:195], v119 offset:64
	s_waitcnt lgkmcnt(1)
	v_mfma_f32_32x32x16_bf16 v[48:63], v[184:187], v[76:79], v[48:63]
	ds_read_b128 v[184:187], v119 offset:96
	s_waitcnt lgkmcnt(1)
	v_mfma_f32_32x32x16_bf16 v[48:63], v[192:195], v[72:75], v[48:63]
	s_waitcnt lgkmcnt(0)
	v_mfma_f32_32x32x16_bf16 v[48:63], v[184:187], v[68:71], v[48:63]
	v_cndmask_b32_e64 v187, 0, v191, s[6:7]
	v_cndmask_b32_e64 v186, 0, v190, s[6:7]
	v_cndmask_b32_e64 v185, 0, v189, s[6:7]
	v_cndmask_b32_e64 v184, 0, v188, s[6:7]
	s_nop 1
	v_mfma_f32_32x32x16_bf16 v[48:63], v[184:187], v[84:87], v[48:63]
	s_cbranch_vccnz .LBB0_365
	v_cmp_lt_u32_e32 vcc, v121, v175
	v_add_u32_e32 v125, 2, v121
	s_nop 8
	v_cndmask_b32_e32 v49, v103, v49, vcc
	v_cmp_le_u32_e32 vcc, v121, v175
	s_nop 1
	v_cndmask_b32_e32 v48, v103, v48, vcc
	v_cmp_le_u32_e32 vcc, v125, v175
	v_add_u32_e32 v125, 3, v121
	s_nop 0
	v_cndmask_b32_e32 v50, v103, v50, vcc
	v_cmp_le_u32_e32 vcc, v125, v175
	v_add_u32_e32 v125, 8, v121
	s_nop 0
	v_cndmask_b32_e32 v51, v103, v51, vcc
	v_cmp_le_u32_e32 vcc, v125, v175
	v_add_u32_e32 v125, 9, v121
	s_nop 0
	v_cndmask_b32_e32 v52, v103, v52, vcc
	v_cmp_le_u32_e32 vcc, v125, v175
	v_add_u32_e32 v125, 10, v121
	s_nop 0
	v_cndmask_b32_e32 v53, v103, v53, vcc
	v_cmp_le_u32_e32 vcc, v125, v175
	v_add_u32_e32 v125, 11, v121
	s_nop 0
	v_cndmask_b32_e32 v54, v103, v54, vcc
	v_cmp_le_u32_e32 vcc, v125, v175
	v_add_u32_e32 v125, 16, v121
	s_nop 0
	v_cndmask_b32_e32 v55, v103, v55, vcc
	v_cmp_le_u32_e32 vcc, v125, v175
	v_add_u32_e32 v125, 17, v121
	s_nop 0
	v_cndmask_b32_e32 v56, v103, v56, vcc
	v_cmp_le_u32_e32 vcc, v125, v175
	v_add_u32_e32 v125, 18, v121
	s_nop 0
	v_cndmask_b32_e32 v57, v103, v57, vcc
	v_cmp_le_u32_e32 vcc, v125, v175
	v_add_u32_e32 v125, 19, v121
	s_nop 0
	v_cndmask_b32_e32 v58, v103, v58, vcc
	v_cmp_le_u32_e32 vcc, v125, v175
	v_add_u32_e32 v125, 24, v121
	s_nop 0
	v_cndmask_b32_e32 v59, v103, v59, vcc
	v_cmp_le_u32_e32 vcc, v125, v175
	v_add_u32_e32 v125, 25, v121
	s_nop 0
	v_cndmask_b32_e32 v60, v103, v60, vcc
	v_cmp_le_u32_e32 vcc, v125, v175
	v_add_u32_e32 v125, 26, v121
	s_nop 0
	v_cndmask_b32_e32 v61, v103, v61, vcc
	v_cmp_le_u32_e32 vcc, v125, v175
	v_add_u32_e32 v125, 27, v121
	s_nop 0
	v_cndmask_b32_e32 v62, v103, v62, vcc
	v_cmp_le_u32_e32 vcc, v125, v175
	s_nop 1
	v_cndmask_b32_e32 v63, v103, v63, vcc

; #define LAS __attribute__((address_space(3)))
; __device__ __forceinline__ int crow(int r, int hi) { return (r & 3) + 8 * (r >> 2) + 4 * hi; }
; __device__ __forceinline__ void attn_unit(const Params& p, LAS unsigned char* lds, int bh, int qb, float mshift, int tid, int lane, int wave) {
;     ...
;             if (jb >= 0 && 64 * jb + 32 * kh > 32 * wave + 31) continue;
;             f32x16 C;
; #pragma unroll
;             for (int i = 0; i < 16; ++i) C[i] = -mshift;
;             const LAS unsigned char* kr = bb + AB_K + (32 * kh + r32) * 144 + hi * 16;
; #pragma unroll
;             for (int d0 = 0; d0 < 4; ++d0) { const bf16x8 a = *(const LAS bf16x8*)(kr + d0 * 32); C = __builtin_amdgcn_mfma_f32_32x32x16_bf16(a, qr[d0], C, 0, 0, 0); }
;             { u32x4 t = *(const LAS u32x4*)(bb + AB_A + (32 * kh + r32) * 16); if (hi) t = (u32x4){0u, 0u, 0u, 0u};
;               C = __builtin_amdgcn_mfma_f32_32x32x16_bf16(__builtin_bit_cast(bf16x8, t), qa, C, 0, 0, 0); }
;             if (jb >= 0) {
; #pragma unroll
;                 for (int i = 0; i < 16; ++i) { const int kv = 64 * jb + 32 * kh + crow(i, hi); if (kv > q_rel) C[i] = -INFINITY; }
;             }
.LBB0_366:
	s_cmp_ge_u32 s49, s4
	s_cselect_b64 s[52:53], -1, 0
	s_and_b64 s[38:39], s[38:39], s[52:53]
	s_and_b64 vcc, exec, s[38:39]
	s_cbranch_vccnz .LBB0_370
	v_add_u32_e32 v123, v123, v180
	ds_read_b128 v[184:187], v123
	ds_read_b128 v[188:191], v123 offset:32
	v_add_u32_e32 v125, s51, v181
	s_add_i32 s54, s49, 64
	s_cmp_le_i32 s54, s4
	s_cselect_b64 vcc, exec, 0
	s_waitcnt lgkmcnt(1)
	v_mfma_f32_32x32x16_bf16 v[48:63], v[184:187], v[80:83], v[0:15]
	s_waitcnt lgkmcnt(0)
	v_mfma_f32_32x32x16_bf16 v[48:63], v[188:191], v[76:79], v[48:63]
	ds_read_b128 v[184:187], v123 offset:64
	ds_read_b128 v[188:191], v123 offset:96
	s_waitcnt lgkmcnt(1)
	v_mfma_f32_32x32x16_bf16 v[48:63], v[184:187], v[72:75], v[48:63]
	ds_read_b128 v[184:187], v125 offset:18432
	s_waitcnt lgkmcnt(0)
	v_cndmask_b32_e64 v187, 0, v187, s[6:7]
	v_cndmask_b32_e64 v186, 0, v186, s[6:7]
	v_mfma_f32_32x32x16_bf16 v[48:63], v[188:191], v[68:71], v[48:63]
	v_cndmask_b32_e64 v185, 0, v185, s[6:7]
	v_cndmask_b32_e64 v184, 0, v184, s[6:7]
	s_nop 1
	v_mfma_f32_32x32x16_bf16 v[48:63], v[184:187], v[84:87], v[48:63]
	s_cbranch_vccnz .LBB0_369
	v_add_u32_e32 v125, 32, v121
	v_cmp_le_u32_e32 vcc, v125, v175
	v_add_u32_e32 v125, 33, v121
	s_nop 7
	v_cndmask_b32_e32 v48, v103, v48, vcc
	v_cmp_le_u32_e32 vcc, v125, v175
	v_add_u32_e32 v125, 34, v121
	s_nop 0
	v_cndmask_b32_e32 v49, v103, v49, vcc
	v_cmp_le_u32_e32 vcc, v125, v175
	v_add_u32_e32 v125, 35, v121
	s_nop 0
	v_cndmask_b32_e32 v50, v103, v50, vcc
	v_cmp_le_u32_e32 vcc, v125, v175
	v_add_u32_e32 v125, 40, v121
	s_nop 0
	v_cndmask_b32_e32 v51, v103, v51, vcc
	v_cmp_le_u32_e32 vcc, v125, v175
	v_add_u32_e32 v125, 41, v121
	s_nop 0
	v_cndmask_b32_e32 v52, v103, v52, vcc
	v_cmp_le_u32_e32 vcc, v125, v175
	v_add_u32_e32 v125, 42, v121
	s_nop 0
	v_cndmask_b32_e32 v53, v103, v53, vcc
	v_cmp_le_u32_e32 vcc, v125, v175
	v_add_u32_e32 v125, 43, v121
	s_nop 0
	v_cndmask_b32_e32 v54, v103, v54, vcc
	v_cmp_le_u32_e32 vcc, v125, v175
	v_add_u32_e32 v125, 48, v121
	s_nop 0
	v_cndmask_b32_e32 v55, v103, v55, vcc
	v_cmp_le_u32_e32 vcc, v125, v175
	v_add_u32_e32 v125, 49, v121
	s_nop 0
	v_cndmask_b32_e32 v56, v103, v56, vcc
	v_cmp_le_u32_e32 vcc, v125, v175
	v_add_u32_e32 v125, 50, v121
	s_nop 0
	v_cndmask_b32_e32 v57, v103, v57, vcc
	v_cmp_le_u32_e32 vcc, v125, v175
	v_add_u32_e32 v125, 51, v121
	s_nop 0
	v_cndmask_b32_e32 v58, v103, v58, vcc
	v_cmp_le_u32_e32 vcc, v125, v175
	v_add_u32_e32 v125, 56, v121
	s_nop 0
	v_cndmask_b32_e32 v59, v103, v59, vcc
	v_cmp_le_u32_e32 vcc, v125, v175
	v_add_u32_e32 v125, 57, v121
	s_nop 0
	v_cndmask_b32_e32 v60, v103, v60, vcc
	v_cmp_le_u32_e32 vcc, v125, v175
	v_add_u32_e32 v125, 58, v121
	v_add_u32_e32 v121, 59, v121
	v_cndmask_b32_e32 v61, v103, v61, vcc
	v_cmp_le_u32_e32 vcc, v125, v175
	s_nop 1
	v_cndmask_b32_e32 v62, v103, v62, vcc
	v_cmp_le_u32_e32 vcc, v121, v175
	s_nop 1
	v_cndmask_b32_e32 v63, v103, v63, vcc
